# w_down f32->bf16 transposition of both layers moved out of the serial weight passes into layer 0 gate/up K-loop (2 row loads per iteration in the load segment, 16-byte stores)
# baseline (speedup 1.0000x reference)
; #define LAS __attribute__((address_space(3)))
; __device__ __forceinline__ void weights_pass(const Args& a, LAS unsigned char* scr, int gw, int NGW, int lane, int pass) {
;     unsigned char* ws = a.ws;
;     constexpr int I_IN = 64 * 72, I_PL = 64, I_OUT = 64 * 64, I_QM = 64 * 8, I_OMI = 8 * 64, I_G = 64 * 172, I_DN = 172 * 64;
;     constexpr int PER_LAYER = I_IN + I_OUT + 3 * I_QM + I_OMI + 2 * I_G + I_DN;
;     for (int it = gw + (pass == 1 ? PER_LAYER : 0); it < (pass == 2 ? PER_LAYER : 2 * PER_LAYER); it += NGW) {
;         const int l = it / PER_LAYER; int r = it % PER_LAYER;
;         { const bool shared = (r >= I_IN + I_OUT / 2 && r < I_IN + I_OUT) || (r >= I_IN + I_OUT + I_QM && r < I_IN + I_OUT + 3 * I_QM);
;           const int ip = (shared || (l == 0 && r < I_IN)) ? 0 : (l == 0 ? 2 : 1);
;           if (ip != pass) continue; }
;         unsigned char* wl = ws + WS_W + (size_t)l * WL_SIZE;
;         if (r < I_IN) { transpose_item<1>(a.in[I_WIN] + (size_t)l * DM * INW, DM, INW, (bf16_t*)(wl + WL_IN), a.in[I_GMIX] + l * DM, nullptr, 0, scr, r, lane); continue; } r -= I_IN;
;         if (r < I_OUT / 2) { transpose_item<0>(a.in[I_WOUT] + (size_t)l * DM * DM, 2048, DM, (bf16_t*)(wl + WL_OUT), nullptr, nullptr, 0, scr, r, lane, DM); continue; } r -= I_OUT / 2;
;         if (r < I_OUT / 2) { transpose_item<0>(a.in[I_WOUT] + (size_t)l * DM * DM + (size_t)2048 * DM, 2048, DM, (bf16_t*)(ws + WS_WLOW) + (size_t)l * DM * 2048, nullptr, nullptr, 0, scr, r, lane); continue; } r -= I_OUT / 2;
;         if (r < I_QM) { transpose_item<0>(a.in[I_WQM] + (size_t)l * DM * MW, DM, MW, (bf16_t*)(wl + WL_Q), a.in[I_GCROSS] + l * DM, nullptr, 0, scr, r, lane); continue; } r -= I_QM;
;         if (r < I_QM) { transpose_item<1>(a.in[I_WKM] + (size_t)l * DM * MW, DM, MW, (bf16_t*)(ws + WS_WKV) + (size_t)l * 1024 * DM, a.in[I_GMEM] + l * DM, nullptr, 0, scr, r, lane); continue; } r -= I_QM;
;         if (r < I_QM) { transpose_item<1>(a.in[I_WVM] + (size_t)l * DM * MW, DM, MW, (bf16_t*)(ws + WS_WKV) + (size_t)l * 1024 * DM, a.in[I_GMEM] + l * DM, nullptr, 512, scr, r, lane); continue; } r -= I_QM;
;         if (r < I_OMI) { transpose_item<0>(a.in[I_WOM] + (size_t)l * MW * DM, MW, DM, (bf16_t*)(wl + WL_OM), nullptr, nullptr, 0, scr, r, lane); continue; } r -= I_OMI;
.LBB0_625:
	s_mul_hi_i32 s0, s8, 0xbfa02fe9
	s_add_i32 s0, s0, s8
	s_lshr_b32 s1, s0, 31
	s_ashr_i32 s0, s0, 15
	s_add_i32 s0, s0, s1
	s_mul_i32 s1, s0, 0xffff5500
	s_add_i32 s20, s8, s1
	s_add_i32 s21, s20, 0xffffe600
	s_cmpk_gt_u32 s21, 0x7ff
	s_cselect_b64 s[2:3], -1, 0
	s_and_b32 s1, s20, 0xfffffc00
	s_cmpk_lg_i32 s1, 0x2400
	s_cselect_b64 s[4:5], -1, 0
	s_and_b64 s[2:3], s[2:3], s[4:5]
	s_cmp_gt_i32 s8, 0xffff5500
	s_cselect_b64 s[4:5], -1, 0
	s_cmpk_gt_i32 s20, 0x11ff
	s_cselect_b64 s[6:7], -1, 0
	s_and_b64 s[4:5], s[4:5], s[6:7]
	s_and_b64 s[2:3], s[2:3], s[4:5]
	s_andn2_b64 vcc, exec, s[2:3]
	s_cbranch_vccnz .LBB0_624
	s_ashr_i32 s1, s0, 31
	s_mul_i32 s3, s0, 0x15000000
	v_readlane_b32 s4, v251, 12
	s_mul_hi_i32 s2, s0, 0x15000000
	s_add_u32 s18, s4, s3
	v_readlane_b32 s3, v251, 13
	s_addc_u32 s19, s3, s2
	s_cmpk_gt_u32 s20, 0x19ff
	s_mov_b64 s[4:5], -1
	s_cbranch_scc0 .LBB0_666
	s_cmpk_gt_u32 s20, 0x21ff
	s_cbranch_scc0 .LBB0_663
	s_cmpk_gt_u32 s20, 0x23ff
	s_cbranch_scc0 .LBB0_658
	s_cmpk_gt_u32 s20, 0x25ff
	s_cbranch_scc0 .LBB0_653
	s_cmpk_gt_u32 s20, 0x27ff
	s_cbranch_scc0 .LBB0_648
	s_cmpk_gt_u32 s20, 0x29ff
	s_cbranch_scc0 .LBB0_645
	s_cmpk_gt_u32 s20, 0x54ff
	s_mul_hi_i32 s2, s0, 0xac00000
	s_mul_i32 s3, s0, 0xac00000
	s_cbranch_scc0 .LBB0_640
	s_cmpk_gt_u32 s20, 0x7fff
	s_cbranch_scc0 .LBB0_635
	v_readlane_b32 s36, v255, 11
	s_nop 3
	s_cmpk_eq_i32 s36, 0x100
	s_cbranch_scc1 .LBB0_624
	v_readlane_b32 s36, v250, 0
	v_readlane_b32 s42, v250, 6
	v_readlane_b32 s43, v250, 7
	s_add_u32 s6, s42, s3
	s_addc_u32 s7, s43, s2
	s_and_b32 s4, s20, 0xffc0
	s_xor_b32 s5, s4, 0x8000
	s_lshl_b32 s4, s20, 6
	v_lshlrev_b32_e32 v4, 2, v69
	s_and_b32 s4, s4, 0xfc0
	v_lshl_or_b32 v4, s5, 14, v4
	v_mov_b32_e32 v5, v2
	v_lshl_add_u64 v[4:5], s[6:7], 0, v[4:5]
	s_lshl_b32 s14, s4, 2
	v_lshl_add_u64 v[4:5], v[4:5], 0, s[14:15]
	v_lshlrev_b32_e32 v6, 2, v68
	v_mov_b32_e32 v7, v2
	v_lshl_add_u64 v[60:61], v[4:5], 0, v[6:7]
	s_movk_i32 s6, 0x4000
	v_add_co_u32_e32 v8, vcc, s6, v60
	s_mov_b32 s6, 0x24000
	s_nop 0
	v_addc_co_u32_e32 v9, vcc, 0, v61, vcc
	global_load_dwordx4 v[4:7], v[60:61], off nt
	s_nop 0
	global_load_dwordx4 v[8:11], v[8:9], off nt
	v_add_co_u32_e32 v12, vcc, s22, v60
	s_lshl_b32 s5, s5, 1
	s_nop 0
	v_addc_co_u32_e32 v13, vcc, 0, v61, vcc
	v_add_co_u32_e32 v16, vcc, s6, v60
	s_mov_b32 s6, 0x40000
	s_nop 0
	v_addc_co_u32_e32 v17, vcc, 0, v61, vcc
	global_load_dwordx4 v[12:15], v[12:13], off nt
	s_nop 0
	global_load_dwordx4 v[16:19], v[16:17], off nt
	v_add_co_u32_e32 v20, vcc, s6, v60
	s_mov_b32 s6, 0x44000
	s_nop 0
	v_addc_co_u32_e32 v21, vcc, 0, v61, vcc
	v_add_co_u32_e32 v24, vcc, s6, v60
	s_mov_b32 s6, 0x60000
	s_nop 0
	v_addc_co_u32_e32 v25, vcc, 0, v61, vcc
	global_load_dwordx4 v[20:23], v[20:21], off nt
	s_nop 0
	global_load_dwordx4 v[24:27], v[24:25], off nt
	v_add_co_u32_e32 v28, vcc, s6, v60
	s_mov_b32 s6, 0x64000
	s_nop 0
	v_addc_co_u32_e32 v29, vcc, 0, v61, vcc
	v_add_co_u32_e32 v32, vcc, s6, v60
	s_mov_b32 s6, 0x80000
	s_nop 0
	v_addc_co_u32_e32 v33, vcc, 0, v61, vcc
	global_load_dwordx4 v[28:31], v[28:29], off nt
	s_nop 0
	global_load_dwordx4 v[32:35], v[32:33], off nt
	v_add_co_u32_e32 v36, vcc, s6, v60
	s_mov_b32 s6, 0x84000
	s_nop 0
	v_addc_co_u32_e32 v37, vcc, 0, v61, vcc
	v_add_co_u32_e32 v40, vcc, s6, v60
	s_mov_b32 s6, 0xa0000
	s_nop 0
	v_addc_co_u32_e32 v41, vcc, 0, v61, vcc
	global_load_dwordx4 v[36:39], v[36:37], off nt
	s_nop 0
	global_load_dwordx4 v[40:43], v[40:41], off nt
	v_add_co_u32_e32 v44, vcc, s6, v60
	s_mov_b32 s6, 0xa4000
	s_nop 0
	v_addc_co_u32_e32 v45, vcc, 0, v61, vcc
	v_add_co_u32_e32 v48, vcc, s6, v60
	s_mov_b32 s6, 0xc0000
	s_nop 0
	v_addc_co_u32_e32 v49, vcc, 0, v61, vcc
	global_load_dwordx4 v[44:47], v[44:45], off nt
	s_nop 0
	global_load_dwordx4 v[48:51], v[48:49], off nt
	v_add_co_u32_e32 v52, vcc, s6, v60
	s_mov_b32 s6, 0xc4000
	s_nop 0
	v_addc_co_u32_e32 v53, vcc, 0, v61, vcc
	v_add_co_u32_e32 v56, vcc, s6, v60
	s_mov_b32 s6, 0xe0000
	s_nop 0
	v_addc_co_u32_e32 v57, vcc, 0, v61, vcc
	global_load_dwordx4 v[52:55], v[52:53], off nt
	s_nop 0
	global_load_dwordx4 v[56:59], v[56:57], off nt
	v_add_co_u32_e32 v62, vcc, s6, v60
	s_mov_b32 s6, 0xe4000
	s_nop 0
	v_addc_co_u32_e32 v63, vcc, 0, v61, vcc
	v_add_co_u32_e32 v64, vcc, s6, v60
	s_add_u32 s6, s18, s5
	s_nop 0
	v_addc_co_u32_e32 v65, vcc, 0, v61, vcc
	global_load_dwordx4 v[60:63], v[62:63], off nt
	s_nop 0
	global_load_dwordx4 v[64:67], v[64:65], off nt
	s_waitcnt vmcnt(0)
; #define LAS __attribute__((address_space(3)))
; #define LDS_WAIT() asm volatile("s_waitcnt lgkmcnt(0)" ::: "memory")
; __device__ __forceinline__ unsigned cvt_pk_bf16(float lo, float hi) { unsigned r; asm volatile("v_cvt_pk_bf16_f32 %0, %1, %2" : "=v"(r) : "v"(lo), "v"(hi)); return r; }
;     ...
; #pragma unroll
;     for (int i = 0; i < 8; ++i)
; #pragma unroll
;         for (int e = 0; e < 4; ++e) *(LAS unsigned*)(scr + (4 * r16 + e) * 128 + ((i ^ (r16 & 7)) * 16) + q * 4) = cvt_pk_bf16(v[2 * i][e], v[2 * i + 1][e]);
;     LDS_WAIT(); asm volatile("" ::: "memory");
;     const int c = lane & 7;
; #pragma unroll
;     for (int j = 0; j < 8; ++j) { const int row = (lane >> 3) + 8 * j; const u32x4 o = *(const LAS u32x4*)(scr + row * 128 + ((c ^ ((row >> 2) & 7)) * 16));
;         const int lc = col_off + n0 + row; int dr;
;         if (MODE == 0) dr = lc;
;         else if (MODE == 1) dr = (lc & ~255) + 128 * ((lc >> 5) & 1) + 32 * ((lc >> 6) & 3) + (lc & 31);
;         else if (MODE == 2) dr = 256 * (lc >> 7) + (lc & 127);
;         else dr = 256 * (lc >> 7) + 128 + (lc & 127);
;         *(u32x4*)(WT + (size_t)dr * (ldt ? ldt : K) + k0 + 8 * c) = o; }
;     LDS_WAIT(); asm volatile("" ::: "memory");
	v_cvt_pk_bf16_f32 v4, v4, v8
	v_add_u32_e32 v8, v71, v73
	ds_write_b32 v8, v4
	v_cvt_pk_bf16_f32 v4, v5, v9
	ds_write_b32 v8, v4 offset:128
	v_cvt_pk_bf16_f32 v4, v6, v10
	ds_write_b32 v8, v4 offset:256
	v_cvt_pk_bf16_f32 v4, v7, v11
	ds_write_b32 v8, v4 offset:384
	v_cvt_pk_bf16_f32 v4, v12, v16
	v_add_u32_e32 v5, v74, v73
	ds_write_b32 v5, v4
	v_cvt_pk_bf16_f32 v4, v13, v17
	ds_write_b32 v5, v4 offset:128
	v_cvt_pk_bf16_f32 v4, v14, v18
	ds_write_b32 v5, v4 offset:256
	v_cvt_pk_bf16_f32 v4, v15, v19
	ds_write_b32 v5, v4 offset:384
	v_cvt_pk_bf16_f32 v4, v20, v24
	v_add_u32_e32 v5, v75, v73
	ds_write_b32 v5, v4
	v_cvt_pk_bf16_f32 v4, v21, v25
	ds_write_b32 v5, v4 offset:128
	v_cvt_pk_bf16_f32 v4, v22, v26
	ds_write_b32 v5, v4 offset:256
	v_cvt_pk_bf16_f32 v4, v23, v27
	ds_write_b32 v5, v4 offset:384
	v_cvt_pk_bf16_f32 v4, v28, v32
	v_add_u32_e32 v5, v76, v73
	ds_write_b32 v5, v4
	v_cvt_pk_bf16_f32 v4, v29, v33
	ds_write_b32 v5, v4 offset:128
	v_cvt_pk_bf16_f32 v4, v30, v34
	ds_write_b32 v5, v4 offset:256
	v_cvt_pk_bf16_f32 v4, v31, v35
	ds_write_b32 v5, v4 offset:384
	v_cvt_pk_bf16_f32 v4, v36, v40
	v_add_u32_e32 v5, v77, v73
	ds_write_b32 v5, v4
	v_cvt_pk_bf16_f32 v4, v37, v41
	ds_write_b32 v5, v4 offset:128
	v_cvt_pk_bf16_f32 v4, v38, v42
	ds_write_b32 v5, v4 offset:256
	v_cvt_pk_bf16_f32 v4, v39, v43
	ds_write_b32 v5, v4 offset:384
	v_cvt_pk_bf16_f32 v4, v44, v48
	v_add_u32_e32 v5, v78, v73
	ds_write_b32 v5, v4
	v_cvt_pk_bf16_f32 v4, v45, v49
	ds_write_b32 v5, v4 offset:128
	v_cvt_pk_bf16_f32 v4, v46, v50
	ds_write_b32 v5, v4 offset:256
	v_cvt_pk_bf16_f32 v4, v47, v51
	ds_write_b32 v5, v4 offset:384
	v_cvt_pk_bf16_f32 v4, v52, v56
	v_add_u32_e32 v5, v79, v73
	ds_write_b32 v5, v4
	v_cvt_pk_bf16_f32 v4, v53, v57
	ds_write_b32 v5, v4 offset:128
	v_cvt_pk_bf16_f32 v4, v54, v58
	ds_write_b32 v5, v4 offset:256
	v_cvt_pk_bf16_f32 v4, v55, v59
	ds_write_b32 v5, v4 offset:384
	v_cvt_pk_bf16_f32 v4, v60, v64
	v_add_u32_e32 v5, v80, v73
	ds_write_b32 v5, v4
	v_cvt_pk_bf16_f32 v4, v61, v65
	ds_write_b32 v5, v4 offset:128
	v_cvt_pk_bf16_f32 v4, v62, v66
	ds_write_b32 v5, v4 offset:256
	v_cvt_pk_bf16_f32 v4, v63, v67
	ds_write_b32 v5, v4 offset:384
	s_addc_u32 s7, s19, 0
	v_lshlrev_b32_e32 v4, 1, v70
	v_mov_b32_e32 v5, v2
	s_waitcnt lgkmcnt(0)
	v_lshl_add_u64 v[4:5], s[6:7], 0, v[4:5]
	s_mov_b64 s[6:7], 0xfa00000
	v_lshl_add_u64 v[12:13], v[4:5], 0, s[6:7]
	v_add_u32_e32 v4, v82, v83
	ds_read_b128 v[4:7], v4
	v_or_b32_e32 v8, s4, v81
	v_mul_u32_u24_e32 v8, 0x2b00, v8
	v_lshlrev_b32_e32 v8, 1, v8
	v_mov_b32_e32 v9, v2
	v_lshl_add_u64 v[14:15], v[12:13], 0, v[8:9]
	v_add_u32_e32 v8, v85, v86
	ds_read_b128 v[8:11], v8
	s_waitcnt lgkmcnt(1)
	global_store_dwordx4 v[14:15], v[4:7], off
	v_readlane_b32 s37, v250, 1
	v_readlane_b32 s38, v250, 2
	v_or_b32_e32 v4, s4, v84
	v_mul_u32_u24_e32 v4, 0x2b00, v4
	v_lshlrev_b32_e32 v4, 1, v4
	v_mov_b32_e32 v5, v2
	v_lshl_add_u64 v[4:5], v[12:13], 0, v[4:5]
	s_waitcnt lgkmcnt(0)
	global_store_dwordx4 v[4:5], v[8:11], off
	v_add_u32_e32 v4, v88, v89
	ds_read_b128 v[4:7], v4
	v_or_b32_e32 v8, s4, v87
	v_mul_u32_u24_e32 v8, 0x2b00, v8
	v_lshlrev_b32_e32 v8, 1, v8
	v_mov_b32_e32 v9, v2
	v_lshl_add_u64 v[14:15], v[12:13], 0, v[8:9]
	v_add_u32_e32 v8, v91, v92
	ds_read_b128 v[8:11], v8
	s_waitcnt lgkmcnt(1)
	global_store_dwordx4 v[14:15], v[4:7], off
	v_readlane_b32 s39, v250, 3
	v_readlane_b32 s40, v250, 4
	v_or_b32_e32 v4, s4, v90
	v_mul_u32_u24_e32 v4, 0x2b00, v4
	v_lshlrev_b32_e32 v4, 1, v4
	v_mov_b32_e32 v5, v2
	v_lshl_add_u64 v[4:5], v[12:13], 0, v[4:5]
	s_waitcnt lgkmcnt(0)
	global_store_dwordx4 v[4:5], v[8:11], off
	v_add_u32_e32 v4, v94, v83
	ds_read_b128 v[4:7], v4
	v_or_b32_e32 v8, s4, v93
	v_mul_u32_u24_e32 v8, 0x2b00, v8
	v_lshlrev_b32_e32 v8, 1, v8
	v_mov_b32_e32 v9, v2
	v_lshl_add_u64 v[14:15], v[12:13], 0, v[8:9]
	v_add_u32_e32 v8, v96, v97
	ds_read_b128 v[8:11], v8
	s_waitcnt lgkmcnt(1)
	global_store_dwordx4 v[14:15], v[4:7], off
	v_readlane_b32 s41, v250, 5
	s_nop 0
	v_or_b32_e32 v4, s4, v95
	v_mul_u32_u24_e32 v4, 0x2b00, v4
	v_lshlrev_b32_e32 v4, 1, v4
	v_mov_b32_e32 v5, v2
	v_lshl_add_u64 v[4:5], v[12:13], 0, v[4:5]
	s_waitcnt lgkmcnt(0)
	global_store_dwordx4 v[4:5], v[8:11], off
	v_add_u32_e32 v4, v99, v100
	ds_read_b128 v[4:7], v4
	v_or_b32_e32 v8, s4, v98
	v_mul_u32_u24_e32 v8, 0x2b00, v8
	v_lshlrev_b32_e32 v8, 1, v8
	v_mov_b32_e32 v9, v2
	v_lshl_add_u64 v[14:15], v[12:13], 0, v[8:9]
	v_add_u32_e32 v8, v102, v103
	ds_read_b128 v[8:11], v8
	s_waitcnt lgkmcnt(1)
	global_store_dwordx4 v[14:15], v[4:7], off
	s_nop 1
	v_or_b32_e32 v4, s4, v101
	v_mul_u32_u24_e32 v4, 0x2b00, v4
	v_lshlrev_b32_e32 v4, 1, v4
	v_mov_b32_e32 v5, v2
	v_lshl_add_u64 v[4:5], v[12:13], 0, v[4:5]
	s_waitcnt lgkmcnt(0)
	global_store_dwordx4 v[4:5], v[8:11], off
	s_waitcnt lgkmcnt(0)
	s_mov_b64 s[4:5], 0

; #define PG8_STAGE(bufoff, gbase, voff) do { _Pragma("unroll") for (int _i = 0; _i < 2; ++_i) \
;         __builtin_amdgcn_global_load_lds((const unsigned*)((const char*)(gbase) + (voff)[_i]), (LAS unsigned*)(lds + (bufoff) + ldsw + _i * 8192), 16, 0, 0); } while (0)
; #define PG8_WAIT_V(n) asm volatile("s_waitcnt vmcnt(" #n ")" ::: "memory")
; #define PG8_BAR __builtin_amdgcn_s_barrier()
; template <class Desc, class Epi, bool ALIGN_EPI>
; __device__ __forceinline__ void gemm_phase(LAS unsigned char* lds, const Desc& D, const Epi& E, int G, int c) {
;     ...
;     PG8_AWAIT(cur);
;     PG8_STAGE(PG8_SB(0, 0), cB, voffB); PG8_STAGE(PG8_SB(0, 1), cB + hstepB, voffB); PG8_STAGE(PG8_SA(0, 0), cA, voffA); PG8_STAGE(PG8_SA(0, 1), cA + hstepA, voffA);
;     if (wr == 1) PG8_BAR;
;     PG8_WAIT_V(2); PG8_BAR;
;     PG8_STAGE(PG8_SB(1, 0), cB + kstep, voffB); PG8_STAGE(PG8_SA(1, 0), cA + kstep, voffA); PG8_STAGE(PG8_SB(1, 1), cB + hstepB + kstep, voffB);
;     PG8_WAIT_V(6); PG8_BAR;
.LBB0_1568:
	s_cmp_lt_i32 s23, 0
	v_mov_b32_e32 v135, v2
	s_cselect_b32 s2, 64, 32
	s_and_b64 s[26:27], s[26:27], exec
	v_lshl_add_u64 v[6:7], s[20:21], 0, v[134:135]
	v_mov_b32_e32 v139, v2
	s_cselect_b32 s69, 2, 1
	s_add_i32 s61, s52, 0x18000
	v_lshl_add_u64 v[8:9], s[20:21], 0, v[138:139]
	v_mov_b32_e32 v133, v2
	v_and_b32_e32 v164, 63, v4
	v_bfe_u32 v165, v4, 4, 2
	v_lshl_add_u64 v[4:5], v[6:7], 0, s[76:77]
	s_mov_b32 m0, s61
	s_add_i32 s62, s52, 0x1a000
	v_lshl_add_u64 v[10:11], s[18:19], 0, v[132:133]
	v_mov_b32_e32 v137, v2
	s_waitcnt vmcnt(2)
	s_barrier
	global_load_lds_dwordx4 v[4:5], off
	v_lshl_add_u64 v[4:5], v[8:9], 0, s[76:77]
	s_mov_b32 m0, s62
	s_add_i32 s63, s52, 0x8000
	s_add_i32 s64, s52, 0xa000
	v_lshl_add_u64 v[12:13], s[18:19], 0, v[136:137]
	global_load_lds_dwordx4 v[4:5], off
	v_lshl_add_u64 v[4:5], v[10:11], 0, s[76:77]
	s_mov_b32 m0, s63
	s_add_u32 s26, s20, 0x100080
	global_load_lds_dwordx4 v[4:5], off
	v_lshl_add_u64 v[4:5], v[12:13], 0, s[76:77]
	s_mov_b32 m0, s64
	s_addc_u32 s27, s21, 0
	s_add_i32 s65, s52, 0x1c000
	global_load_lds_dwordx4 v[4:5], off
	v_lshl_add_u64 v[4:5], s[26:27], 0, v[134:135]
	s_mov_b32 m0, s65
	s_add_i32 s67, s52, 0x1e000
	global_load_lds_dwordx4 v[4:5], off
	v_lshl_add_u64 v[4:5], s[26:27], 0, v[138:139]
	s_mov_b32 m0, s67
	s_cmpk_lt_u32 s3, 0x100
	global_load_lds_dwordx4 v[4:5], off
	s_waitcnt vmcnt(6)
	s_mov_b32 s60, 0
	s_cselect_b64 s[26:27], -1, 0
	s_mov_b64 s[42:43], s[18:19]
	s_barrier
	s_mov_b32 s53, 0
	v_readlane_b32 s54, v255, 31
	v_readlane_b32 s55, v255, 11
	s_nop 3
	s_cmp_lg_u32 s54, 0
	s_cbranch_scc1 .Lbg_setup_done
	s_cmpk_lg_i32 s55, 0x100
	s_cbranch_scc1 .Lbg_setup_done
	s_mov_b32 s53, 1
	s_lshr_b32 s54, s52, 10
	s_lshl_b32 s55, s82, 3
	s_add_i32 s54, s54, s55
	s_and_b32 s55, s54, 63
	s_lshr_b32 s54, s54, 6
	v_readlane_b32 s56, v250, 6
	v_readlane_b32 s57, v250, 7
	s_lshl_b32 s58, s54, 17
	s_lshl_b32 s59, s55, 8
	s_add_i32 s58, s58, s59
	s_nop 3
	s_add_u32 s56, s56, s58
	s_addc_u32 s57, s57, 0
	v_readlane_b32 s58, v251, 12
	v_readlane_b32 s59, v251, 13
	s_lshl_b32 s61, s54, 4
	s_add_i32 s61, s61, 0xfa00000
	s_nop 3
	s_add_u32 s58, s58, s61
	s_addc_u32 s59, s59, 0
	v_lshlrev_b32_e32 v227, 2, v164
	s_lshl_b32 s61, s55, 6
	v_add_u32_e32 v228, s61, v164
	v_mul_u32_u24_e32 v228, 0x5600, v228
	s_mov_b32 s54, 0
	s_mov_b32 s55, 0
.Lbg_setup_done:
	s_branch .LBB0_1571
.LBB0_1569:
	s_mov_b64 s[12:13], 0

; #define PG8_STAGE(bufoff, gbase, voff) do { _Pragma("unroll") for (int _i = 0; _i < 2; ++_i) \
;         __builtin_amdgcn_global_load_lds((const unsigned*)((const char*)(gbase) + (voff)[_i]), (LAS unsigned*)(lds + (bufoff) + ldsw + _i * 8192), 16, 0, 0); } while (0)
; #define PG8_LDA(dst, b, h) do { _Pragma("unroll") for (int m = 0; m < 4; ++m) _Pragma("unroll") for (int k = 0; k < 2; ++k) dst[m][k] = *(const LAS bf16x8*)(pA + PG8_SA(b, h) + m * 2048 + k * 1024); } while (0)
; #define PG8_LDB(dst, b, h) do { _Pragma("unroll") for (int n = 0; n < 2; ++n) _Pragma("unroll") for (int k = 0; k < 2; ++k) dst[n][k] = *(const LAS bf16x8*)(pB + (PG8_SB(b, h) - 4 * HTB) + n * 2048 + k * 1024); } while (0)
; #define PG8_MMA(ai, bj, At, Bt) do { __builtin_amdgcn_s_setprio(1); _Pragma("unroll") for (int m = 0; m < 4; ++m) _Pragma("unroll") for (int n = 0; n < 2; ++n) _Pragma("unroll") for (int k = 0; k < 2; ++k) \
;         acc[ai][bj][m][n] = __builtin_amdgcn_mfma_f32_16x16x32_bf16(Bt[n][k], At[m][k], acc[ai][bj][m][n], 0, 0, 0); __builtin_amdgcn_s_setprio(0); } while (0)
; #define PG8_WAIT_V(n) asm volatile("s_waitcnt vmcnt(" #n ")" ::: "memory")
; #define PG8_WAIT_L(n) asm volatile("s_waitcnt lgkmcnt(" #n ")" ::: "memory")
; #define PG8_BAR __builtin_amdgcn_s_barrier()
; #define PG8_SCHED __builtin_amdgcn_sched_barrier(0)
; template <class Desc, class Epi, bool ALIGN_EPI>
; __device__ __forceinline__ void gemm_phase(LAS unsigned char* lds, const Desc& D, const Epi& E, int G, int c) {
;     ...
;             PG8_LDB(B0, 0, 0); PG8_LDB(B1, 0, 1); PG8_SCHED; PG8_LDA(At, 0, 0); PG8_STAGE(PG8_SA(1, 1), a1 + hstepA, voffA);
;             PG8_WAIT_V(8); PG8_WAIT_L(0); PG8_BAR; PG8_MMA(0, 0, At, B0); PG8_MMA(0, 1, At, B1); PG8_BAR; PG8_SCHED;
;             PG8_LDA(At, 0, 1); PG8_STAGE(PG8_SB(0, 0), b2, voffB); PG8_STAGE(PG8_SB(0, 1), b2 + hstepB, voffB); PG8_STAGE(PG8_SA(0, 0), a2, voffA);
;             PG8_WAIT_V(8); PG8_WAIT_L(0); PG8_BAR; PG8_MMA(1, 0, At, B0); PG8_MMA(1, 1, At, B1); PG8_BAR; PG8_SCHED;
.LBB0_1580:
	s_or_b32 s14, s30, 1
	s_add_i32 s30, s30, 2
	s_mov_b32 s31, s15
	s_lshl_b64 s[72:73], s[14:15], 7
	s_lshl_b64 s[74:75], s[30:31], 7
	s_add_u32 s14, s18, s74
	ds_read_b128 v[140:143], v163
	ds_read_b128 v[144:147], v163 offset:1024
	ds_read_b128 v[148:151], v163 offset:2048
	ds_read_b128 v[152:155], v163 offset:3072
	ds_read_b128 v[156:159], v163 offset:16384
	ds_read_b128 v[166:169], v163 offset:17408
	ds_read_b128 v[170:173], v163 offset:18432
	ds_read_b128 v[174:177], v163 offset:19456
	s_addc_u32 s31, s19, s75
	s_and_b64 s[46:47], s[34:35], exec
	s_cselect_b32 s47, s43, s31
	s_cselect_b32 s46, s42, s14
	s_add_u32 s14, s20, s74
	s_addc_u32 s31, s21, s75
	s_and_b64 s[34:35], s[34:35], exec
	s_cselect_b32 s35, s3, s31
	s_cselect_b32 s34, s13, s14
	s_add_u32 s14, s18, s72
	s_addc_u32 s31, s19, s73
	s_add_u32 s72, s14, 0x100000
	s_addc_u32 s73, s31, 0
	s_add_i32 m0, s52, 0xc000
	ds_read_b128 v[178:181], v162
	ds_read_b128 v[182:185], v162 offset:1024
	ds_read_b128 v[186:189], v162 offset:2048
	ds_read_b128 v[190:193], v162 offset:3072
	ds_read_b128 v[194:197], v162 offset:4096
	ds_read_b128 v[198:201], v162 offset:5120
	ds_read_b128 v[202:205], v162 offset:6144
	ds_read_b128 v[206:209], v162 offset:7168
	global_load_lds_dwordx4 v132, s[72:73]
	s_add_i32 m0, s52, 0xe000
	s_nop 0
	global_load_lds_dwordx4 v136, s[72:73]
	s_waitcnt vmcnt(8)
	s_waitcnt lgkmcnt(0)
	s_cmp_lg_u32 s53, 1
	s_cbranch_scc1 .Lbg_skip
	s_cmp_lg_u32 s54, 0
	s_cbranch_scc1 .Lbg_load
	s_cmp_eq_u32 s55, 0
	s_cbranch_scc1 .Lbg_nostore
	v_cvt_pk_bf16_f32 v218, v218, v219
	v_cvt_pk_bf16_f32 v219, v220, v221
	v_cvt_pk_bf16_f32 v220, v222, v223
	v_cvt_pk_bf16_f32 v221, v224, v225
	global_store_dwordx4 v228, v[218:221], s[58:59]
	s_add_u32 s58, s58, 0x200
	s_addc_u32 s59, s59, 0
.Lbg_nostore:
	s_cmp_lg_u32 s55, 43
	s_cbranch_scc1 .Lbg_nolayer
	s_add_u32 s58, s58, 0x14ffaa00
	s_addc_u32 s59, s59, 0
.Lbg_nolayer:
	s_cmp_lg_u32 s55, 86
	s_cbranch_scc1 .Lbg_start
	s_mov_b32 s53, 2
	s_branch .Lbg_skip
.Lbg_start:
	s_add_i32 s55, s55, 1
.Lbg_load:
	s_cmp_eq_u32 s54, 0
	s_cbranch_scc0 .Lbg_l1
	global_load_dword v218, v227, s[56:57] nt
	s_add_u32 s56, s56, 0x4000
	s_addc_u32 s57, s57, 0
	global_load_dword v219, v227, s[56:57] nt
	s_add_u32 s56, s56, 0x4000
	s_addc_u32 s57, s57, 0
	s_add_i32 s54, s54, 1
	s_branch .Lbg_skip
.Lbg_l1:
	s_cmp_eq_u32 s54, 1
	s_cbranch_scc0 .Lbg_l2
	global_load_dword v220, v227, s[56:57] nt
	s_add_u32 s56, s56, 0x4000
	s_addc_u32 s57, s57, 0
	global_load_dword v221, v227, s[56:57] nt
	s_add_u32 s56, s56, 0x4000
	s_addc_u32 s57, s57, 0
	s_add_i32 s54, s54, 1
	s_branch .Lbg_skip
.Lbg_l2:
	s_cmp_eq_u32 s54, 2
	s_cbranch_scc0 .Lbg_l3
	global_load_dword v222, v227, s[56:57] nt
	s_add_u32 s56, s56, 0x4000
	s_addc_u32 s57, s57, 0
	global_load_dword v223, v227, s[56:57] nt
	s_add_u32 s56, s56, 0x4000
	s_addc_u32 s57, s57, 0
	s_add_i32 s54, s54, 1
	s_branch .Lbg_skip
.Lbg_l3:
	global_load_dword v224, v227, s[56:57] nt
	s_add_u32 s56, s56, 0x4000
	s_addc_u32 s57, s57, 0
	global_load_dword v225, v227, s[56:57] nt
	s_add_u32 s56, s56, 0x4000
	s_addc_u32 s57, s57, 0
	s_mov_b32 s54, 0
	s_add_u32 s56, s56, 0x3e0000
	s_addc_u32 s57, s57, 0
.Lbg_skip:
	s_barrier
	v_mfma_f32_16x16x32_bf16 v[128:131], v[140:143], v[178:181], v[128:131]
	v_mfma_f32_16x16x32_bf16 v[124:127], v[148:151], v[178:181], v[124:127]
	v_mfma_f32_16x16x32_bf16 v[120:123], v[140:143], v[186:189], v[120:123]
	v_mfma_f32_16x16x32_bf16 v[116:119], v[148:151], v[186:189], v[116:119]
	v_mfma_f32_16x16x32_bf16 v[112:115], v[140:143], v[194:197], v[112:115]
	v_mfma_f32_16x16x32_bf16 v[108:111], v[148:151], v[194:197], v[108:111]
	v_mfma_f32_16x16x32_bf16 v[104:107], v[140:143], v[202:205], v[104:107]
	v_mfma_f32_16x16x32_bf16 v[100:103], v[148:151], v[202:205], v[100:103]
	v_mfma_f32_16x16x32_bf16 v[128:131], v[144:147], v[182:185], v[128:131]
	v_mfma_f32_16x16x32_bf16 v[124:127], v[152:155], v[182:185], v[124:127]
	v_mfma_f32_16x16x32_bf16 v[120:123], v[144:147], v[190:193], v[120:123]
	v_mfma_f32_16x16x32_bf16 v[116:119], v[152:155], v[190:193], v[116:119]
	v_mfma_f32_16x16x32_bf16 v[112:115], v[144:147], v[198:201], v[112:115]
	v_mfma_f32_16x16x32_bf16 v[108:111], v[152:155], v[198:201], v[108:111]
	v_mfma_f32_16x16x32_bf16 v[104:107], v[144:147], v[206:209], v[104:107]
	v_mfma_f32_16x16x32_bf16 v[100:103], v[152:155], v[206:209], v[100:103]
	v_mfma_f32_16x16x32_bf16 v[96:99], v[156:159], v[178:181], v[96:99]
	v_mfma_f32_16x16x32_bf16 v[92:95], v[170:173], v[178:181], v[92:95]
	v_mfma_f32_16x16x32_bf16 v[88:91], v[156:159], v[186:189], v[88:91]
	v_mfma_f32_16x16x32_bf16 v[84:87], v[170:173], v[186:189], v[84:87]
	v_mfma_f32_16x16x32_bf16 v[80:83], v[156:159], v[194:197], v[80:83]
	v_mfma_f32_16x16x32_bf16 v[76:79], v[170:173], v[194:197], v[76:79]
	v_mfma_f32_16x16x32_bf16 v[72:75], v[156:159], v[202:205], v[72:75]
	v_mfma_f32_16x16x32_bf16 v[68:71], v[170:173], v[202:205], v[68:71]
	v_mfma_f32_16x16x32_bf16 v[96:99], v[166:169], v[182:185], v[96:99]
	v_mfma_f32_16x16x32_bf16 v[92:95], v[174:177], v[182:185], v[92:95]
	v_mfma_f32_16x16x32_bf16 v[88:91], v[166:169], v[190:193], v[88:91]
	v_mfma_f32_16x16x32_bf16 v[84:87], v[174:177], v[190:193], v[84:87]
	v_mfma_f32_16x16x32_bf16 v[80:83], v[166:169], v[198:201], v[80:83]
	v_mfma_f32_16x16x32_bf16 v[76:79], v[174:177], v[198:201], v[76:79]
	v_mfma_f32_16x16x32_bf16 v[72:75], v[166:169], v[206:209], v[72:75]
	v_mfma_f32_16x16x32_bf16 v[68:71], v[174:177], v[206:209], v[68:71]
	s_barrier
	s_add_i32 m0, s52, 0x10000
	s_add_u32 s72, s34, 0x100000
	s_addc_u32 s73, s35, 0
	ds_read_b128 v[178:181], v162 offset:16384
	ds_read_b128 v[182:185], v162 offset:17408
	ds_read_b128 v[186:189], v162 offset:18432
	ds_read_b128 v[190:193], v162 offset:19456
	ds_read_b128 v[194:197], v162 offset:20480
	ds_read_b128 v[198:201], v162 offset:21504
	ds_read_b128 v[202:205], v162 offset:22528
	ds_read_b128 v[206:209], v162 offset:23552
	global_load_lds_dwordx4 v134, s[34:35]
	s_add_i32 m0, s52, 0x12000
	s_nop 0
	global_load_lds_dwordx4 v138, s[34:35]
	s_add_i32 m0, s52, 0x14000
	s_nop 0
	global_load_lds_dwordx4 v134, s[72:73]
	s_add_i32 m0, s52, 0x16000
	s_nop 0
	global_load_lds_dwordx4 v138, s[72:73]
	s_mov_b32 m0, s52
	s_nop 0
	global_load_lds_dwordx4 v132, s[46:47]
	s_add_i32 m0, s52, 0x2000
	s_nop 0
	global_load_lds_dwordx4 v136, s[46:47]
	s_cmp_eq_u32 s53, 1
	s_cbranch_scc1 .Lbgw2_a
	s_waitcnt vmcnt(8)
	s_branch .Lbgw2_d
; #define PG8_STAGE(bufoff, gbase, voff) do { _Pragma("unroll") for (int _i = 0; _i < 2; ++_i) \
;         __builtin_amdgcn_global_load_lds((const unsigned*)((const char*)(gbase) + (voff)[_i]), (LAS unsigned*)(lds + (bufoff) + ldsw + _i * 8192), 16, 0, 0); } while (0)
; #define PG8_LDA(dst, b, h) do { _Pragma("unroll") for (int m = 0; m < 4; ++m) _Pragma("unroll") for (int k = 0; k < 2; ++k) dst[m][k] = *(const LAS bf16x8*)(pA + PG8_SA(b, h) + m * 2048 + k * 1024); } while (0)
; #define PG8_LDB(dst, b, h) do { _Pragma("unroll") for (int n = 0; n < 2; ++n) _Pragma("unroll") for (int k = 0; k < 2; ++k) dst[n][k] = *(const LAS bf16x8*)(pB + (PG8_SB(b, h) - 4 * HTB) + n * 2048 + k * 1024); } while (0)
; #define PG8_MMA(ai, bj, At, Bt) do { __builtin_amdgcn_s_setprio(1); _Pragma("unroll") for (int m = 0; m < 4; ++m) _Pragma("unroll") for (int n = 0; n < 2; ++n) _Pragma("unroll") for (int k = 0; k < 2; ++k) \
;         acc[ai][bj][m][n] = __builtin_amdgcn_mfma_f32_16x16x32_bf16(Bt[n][k], At[m][k], acc[ai][bj][m][n], 0, 0, 0); __builtin_amdgcn_s_setprio(0); } while (0)
; #define PG8_WAIT_V(n) asm volatile("s_waitcnt vmcnt(" #n ")" ::: "memory")
; #define PG8_WAIT_L(n) asm volatile("s_waitcnt lgkmcnt(" #n ")" ::: "memory")
; #define PG8_BAR __builtin_amdgcn_s_barrier()
; #define PG8_SCHED __builtin_amdgcn_sched_barrier(0)
; template <class Desc, class Epi, bool ALIGN_EPI>
; __device__ __forceinline__ void gemm_phase(LAS unsigned char* lds, const Desc& D, const Epi& E, int G, int c) {
;     ...
;             PG8_WAIT_V(8); PG8_WAIT_L(0); PG8_BAR; PG8_MMA(1, 0, At, B0); PG8_MMA(1, 1, At, B1); PG8_BAR; PG8_SCHED;
;             PG8_LDB(B0, 1, 0); PG8_LDB(B1, 1, 1); PG8_SCHED; PG8_LDA(At, 1, 0); PG8_STAGE(PG8_SA(0, 1), a2 + hstepA, voffA);
;             PG8_WAIT_V(8); PG8_WAIT_L(0); PG8_BAR; PG8_MMA(0, 0, At, B0); PG8_MMA(0, 1, At, B1); PG8_BAR; PG8_SCHED;
;             PG8_LDA(At, 1, 1); PG8_STAGE(PG8_SB(1, 0), b3, voffB); PG8_STAGE(PG8_SB(1, 1), b3 + hstepB, voffB); PG8_STAGE(PG8_SA(1, 0), a3, voffA);
.Lbgw2_a:
	s_waitcnt vmcnt(10)
.Lbgw2_d:
	s_waitcnt lgkmcnt(0)
	s_barrier
	v_mfma_f32_16x16x32_bf16 v[64:67], v[140:143], v[178:181], v[64:67]
	v_mfma_f32_16x16x32_bf16 v[52:55], v[148:151], v[178:181], v[52:55]
	v_mfma_f32_16x16x32_bf16 v[32:35], v[140:143], v[186:189], v[32:35]
	v_mfma_f32_16x16x32_bf16 v[20:23], v[148:151], v[186:189], v[20:23]
	v_mfma_f32_16x16x32_bf16 v[16:19], v[140:143], v[194:197], v[16:19]
	v_mfma_f32_16x16x32_bf16 v[12:15], v[148:151], v[194:197], v[12:15]
	v_mfma_f32_16x16x32_bf16 v[8:11], v[140:143], v[202:205], v[8:11]
	v_mfma_f32_16x16x32_bf16 v[4:7], v[148:151], v[202:205], v[4:7]
	v_mfma_f32_16x16x32_bf16 v[64:67], v[144:147], v[182:185], v[64:67]
	v_mfma_f32_16x16x32_bf16 v[52:55], v[152:155], v[182:185], v[52:55]
	v_mfma_f32_16x16x32_bf16 v[32:35], v[144:147], v[190:193], v[32:35]
	v_mfma_f32_16x16x32_bf16 v[20:23], v[152:155], v[190:193], v[20:23]
	v_mfma_f32_16x16x32_bf16 v[16:19], v[144:147], v[198:201], v[16:19]
	v_mfma_f32_16x16x32_bf16 v[12:15], v[152:155], v[198:201], v[12:15]
	v_mfma_f32_16x16x32_bf16 v[8:11], v[144:147], v[206:209], v[8:11]
	v_mfma_f32_16x16x32_bf16 v[4:7], v[152:155], v[206:209], v[4:7]
	v_mfma_f32_16x16x32_bf16 v[60:63], v[156:159], v[178:181], v[60:63]
	v_mfma_f32_16x16x32_bf16 v[56:59], v[170:173], v[178:181], v[56:59]
	v_mfma_f32_16x16x32_bf16 v[48:51], v[156:159], v[186:189], v[48:51]
	v_mfma_f32_16x16x32_bf16 v[44:47], v[170:173], v[186:189], v[44:47]
	v_mfma_f32_16x16x32_bf16 v[40:43], v[156:159], v[194:197], v[40:43]
	v_mfma_f32_16x16x32_bf16 v[36:39], v[170:173], v[194:197], v[36:39]
	v_mfma_f32_16x16x32_bf16 v[28:31], v[156:159], v[202:205], v[28:31]
	v_mfma_f32_16x16x32_bf16 v[24:27], v[170:173], v[202:205], v[24:27]
	v_mfma_f32_16x16x32_bf16 v[60:63], v[166:169], v[182:185], v[60:63]
	v_mfma_f32_16x16x32_bf16 v[56:59], v[174:177], v[182:185], v[56:59]
	v_mfma_f32_16x16x32_bf16 v[48:51], v[166:169], v[190:193], v[48:51]
	v_mfma_f32_16x16x32_bf16 v[44:47], v[174:177], v[190:193], v[44:47]
	v_mfma_f32_16x16x32_bf16 v[40:43], v[166:169], v[198:201], v[40:43]
	v_mfma_f32_16x16x32_bf16 v[36:39], v[174:177], v[198:201], v[36:39]
	v_mfma_f32_16x16x32_bf16 v[28:31], v[166:169], v[206:209], v[28:31]
	v_mfma_f32_16x16x32_bf16 v[24:27], v[174:177], v[206:209], v[24:27]
	s_barrier
	ds_read_b128 v[140:143], v163 offset:32768
	ds_read_b128 v[144:147], v163 offset:33792
	ds_read_b128 v[148:151], v163 offset:34816
	ds_read_b128 v[152:155], v163 offset:35840
	ds_read_b128 v[156:159], v163 offset:49152
	ds_read_b128 v[166:169], v163 offset:50176
	ds_read_b128 v[170:173], v163 offset:51200
	ds_read_b128 v[174:177], v163 offset:52224
	s_add_u32 s46, s46, 0x100000
	s_addc_u32 s47, s47, 0
	s_add_i32 m0, s52, 0x4000
	ds_read_b128 v[178:181], v162 offset:32768
	ds_read_b128 v[182:185], v162 offset:33792
	ds_read_b128 v[186:189], v162 offset:34816
	ds_read_b128 v[190:193], v162 offset:35840
	ds_read_b128 v[194:197], v162 offset:36864
	ds_read_b128 v[198:201], v162 offset:37888
	ds_read_b128 v[202:205], v162 offset:38912
	ds_read_b128 v[206:209], v162 offset:39936
	global_load_lds_dwordx4 v132, s[46:47]
	s_add_i32 m0, s52, 0x6000
	s_nop 0
	global_load_lds_dwordx4 v136, s[46:47]
	s_cmp_eq_u32 s53, 1
	s_cbranch_scc1 .Lbgw3_a
	s_waitcnt vmcnt(8)
	s_branch .Lbgw3_d

; #define PG8_STAGE(bufoff, gbase, voff) do { _Pragma("unroll") for (int _i = 0; _i < 2; ++_i) \
;         __builtin_amdgcn_global_load_lds((const unsigned*)((const char*)(gbase) + (voff)[_i]), (LAS unsigned*)(lds + (bufoff) + ldsw + _i * 8192), 16, 0, 0); } while (0)
; #define PG8_LDA(dst, b, h) do { _Pragma("unroll") for (int m = 0; m < 4; ++m) _Pragma("unroll") for (int k = 0; k < 2; ++k) dst[m][k] = *(const LAS bf16x8*)(pA + PG8_SA(b, h) + m * 2048 + k * 1024); } while (0)
; #define PG8_MMA(ai, bj, At, Bt) do { __builtin_amdgcn_s_setprio(1); _Pragma("unroll") for (int m = 0; m < 4; ++m) _Pragma("unroll") for (int n = 0; n < 2; ++n) _Pragma("unroll") for (int k = 0; k < 2; ++k) \
;         acc[ai][bj][m][n] = __builtin_amdgcn_mfma_f32_16x16x32_bf16(Bt[n][k], At[m][k], acc[ai][bj][m][n], 0, 0, 0); __builtin_amdgcn_s_setprio(0); } while (0)
; #define PG8_WAIT_V(n) asm volatile("s_waitcnt vmcnt(" #n ")" ::: "memory")
; #define PG8_WAIT_L(n) asm volatile("s_waitcnt lgkmcnt(" #n ")" ::: "memory")
; #define PG8_BAR __builtin_amdgcn_s_barrier()
; #define PG8_SCHED __builtin_amdgcn_sched_barrier(0)
; template <class Desc, class Epi, bool ALIGN_EPI>
; __device__ __forceinline__ void gemm_phase(LAS unsigned char* lds, const Desc& D, const Epi& E, int G, int c) {
;     ...
;             PG8_WAIT_V(8); PG8_WAIT_L(0); PG8_BAR; PG8_MMA(0, 0, At, B0); PG8_MMA(0, 1, At, B1); PG8_BAR; PG8_SCHED;
;             PG8_LDA(At, 1, 1); PG8_STAGE(PG8_SB(1, 0), b3, voffB); PG8_STAGE(PG8_SB(1, 1), b3 + hstepB, voffB); PG8_STAGE(PG8_SA(1, 0), a3, voffA);
;             PG8_WAIT_V(8); PG8_WAIT_L(0); PG8_BAR; PG8_MMA(1, 0, At, B0); PG8_MMA(1, 1, At, B1); PG8_BAR; PG8_SCHED;
;         }
.Lbgw3_d:
	s_waitcnt lgkmcnt(0)
	s_barrier
	v_mfma_f32_16x16x32_bf16 v[128:131], v[140:143], v[178:181], v[128:131]
	v_mfma_f32_16x16x32_bf16 v[124:127], v[148:151], v[178:181], v[124:127]
	v_mfma_f32_16x16x32_bf16 v[120:123], v[140:143], v[186:189], v[120:123]
	v_mfma_f32_16x16x32_bf16 v[116:119], v[148:151], v[186:189], v[116:119]
	v_mfma_f32_16x16x32_bf16 v[112:115], v[140:143], v[194:197], v[112:115]
	v_mfma_f32_16x16x32_bf16 v[108:111], v[148:151], v[194:197], v[108:111]
	v_mfma_f32_16x16x32_bf16 v[104:107], v[140:143], v[202:205], v[104:107]
	v_mfma_f32_16x16x32_bf16 v[100:103], v[148:151], v[202:205], v[100:103]
	v_mfma_f32_16x16x32_bf16 v[128:131], v[144:147], v[182:185], v[128:131]
	v_mfma_f32_16x16x32_bf16 v[124:127], v[152:155], v[182:185], v[124:127]
	v_mfma_f32_16x16x32_bf16 v[120:123], v[144:147], v[190:193], v[120:123]
	v_mfma_f32_16x16x32_bf16 v[116:119], v[152:155], v[190:193], v[116:119]
	v_mfma_f32_16x16x32_bf16 v[112:115], v[144:147], v[198:201], v[112:115]
	v_mfma_f32_16x16x32_bf16 v[108:111], v[152:155], v[198:201], v[108:111]
	v_mfma_f32_16x16x32_bf16 v[104:107], v[144:147], v[206:209], v[104:107]
	v_mfma_f32_16x16x32_bf16 v[100:103], v[152:155], v[206:209], v[100:103]
	v_mfma_f32_16x16x32_bf16 v[96:99], v[156:159], v[178:181], v[96:99]
	v_mfma_f32_16x16x32_bf16 v[92:95], v[170:173], v[178:181], v[92:95]
	v_mfma_f32_16x16x32_bf16 v[88:91], v[156:159], v[186:189], v[88:91]
	v_mfma_f32_16x16x32_bf16 v[84:87], v[170:173], v[186:189], v[84:87]
	v_mfma_f32_16x16x32_bf16 v[80:83], v[156:159], v[194:197], v[80:83]
	v_mfma_f32_16x16x32_bf16 v[76:79], v[170:173], v[194:197], v[76:79]
	v_mfma_f32_16x16x32_bf16 v[72:75], v[156:159], v[202:205], v[72:75]
	v_mfma_f32_16x16x32_bf16 v[68:71], v[170:173], v[202:205], v[68:71]
	v_mfma_f32_16x16x32_bf16 v[96:99], v[166:169], v[182:185], v[96:99]
	v_mfma_f32_16x16x32_bf16 v[92:95], v[174:177], v[182:185], v[92:95]
	v_mfma_f32_16x16x32_bf16 v[88:91], v[166:169], v[190:193], v[88:91]
	v_mfma_f32_16x16x32_bf16 v[84:87], v[174:177], v[190:193], v[84:87]
	v_mfma_f32_16x16x32_bf16 v[80:83], v[166:169], v[198:201], v[80:83]
	v_mfma_f32_16x16x32_bf16 v[76:79], v[174:177], v[198:201], v[76:79]
	v_mfma_f32_16x16x32_bf16 v[72:75], v[166:169], v[206:209], v[72:75]
	v_mfma_f32_16x16x32_bf16 v[68:71], v[174:177], v[206:209], v[68:71]
	s_barrier
	s_add_i32 m0, s52, 0x18000
	s_add_u32 s74, s34, 0x80
	s_addc_u32 s75, s35, 0
	s_add_u32 s34, s34, 0x100080
	s_addc_u32 s35, s35, 0
	ds_read_b128 v[178:181], v162 offset:49152
	ds_read_b128 v[182:185], v162 offset:50176
	ds_read_b128 v[186:189], v162 offset:51200
	ds_read_b128 v[190:193], v162 offset:52224
	ds_read_b128 v[194:197], v162 offset:53248
	ds_read_b128 v[198:201], v162 offset:54272
	ds_read_b128 v[202:205], v162 offset:55296
	ds_read_b128 v[206:209], v162 offset:56320
	global_load_lds_dwordx4 v134, s[74:75]
	s_add_i32 m0, s52, 0x1a000
	s_nop 0
	global_load_lds_dwordx4 v138, s[74:75]
	s_add_i32 m0, s52, 0x1c000
	s_nop 0
	global_load_lds_dwordx4 v134, s[34:35]
	s_add_i32 m0, s52, 0x1e000
	s_nop 0
	global_load_lds_dwordx4 v138, s[34:35]
	s_sub_u32 s74, s46, 0xfff80
	s_subb_u32 s75, s47, 0
	s_add_i32 m0, s52, 0x8000
	s_nop 0
	global_load_lds_dwordx4 v132, s[74:75]
	s_add_i32 m0, s52, 0xa000
	s_nop 0
	global_load_lds_dwordx4 v136, s[74:75]
	s_waitcnt vmcnt(8)
	s_waitcnt lgkmcnt(0)
	s_barrier
	v_mfma_f32_16x16x32_bf16 v[64:67], v[140:143], v[178:181], v[64:67]
	v_mfma_f32_16x16x32_bf16 v[52:55], v[148:151], v[178:181], v[52:55]
	v_mfma_f32_16x16x32_bf16 v[32:35], v[140:143], v[186:189], v[32:35]
	v_mfma_f32_16x16x32_bf16 v[20:23], v[148:151], v[186:189], v[20:23]
	v_mfma_f32_16x16x32_bf16 v[16:19], v[140:143], v[194:197], v[16:19]
	v_mfma_f32_16x16x32_bf16 v[12:15], v[148:151], v[194:197], v[12:15]
	v_mfma_f32_16x16x32_bf16 v[8:11], v[140:143], v[202:205], v[8:11]
	v_mfma_f32_16x16x32_bf16 v[4:7], v[148:151], v[202:205], v[4:7]
	v_mfma_f32_16x16x32_bf16 v[64:67], v[144:147], v[182:185], v[64:67]
	v_mfma_f32_16x16x32_bf16 v[52:55], v[152:155], v[182:185], v[52:55]
	v_mfma_f32_16x16x32_bf16 v[32:35], v[144:147], v[190:193], v[32:35]
	v_mfma_f32_16x16x32_bf16 v[20:23], v[152:155], v[190:193], v[20:23]
	v_mfma_f32_16x16x32_bf16 v[16:19], v[144:147], v[198:201], v[16:19]
	v_mfma_f32_16x16x32_bf16 v[12:15], v[152:155], v[198:201], v[12:15]
	v_mfma_f32_16x16x32_bf16 v[8:11], v[144:147], v[206:209], v[8:11]
	v_mfma_f32_16x16x32_bf16 v[4:7], v[152:155], v[206:209], v[4:7]
	v_mfma_f32_16x16x32_bf16 v[60:63], v[156:159], v[178:181], v[60:63]
	v_mfma_f32_16x16x32_bf16 v[56:59], v[170:173], v[178:181], v[56:59]
	v_mfma_f32_16x16x32_bf16 v[48:51], v[156:159], v[186:189], v[48:51]
	v_mfma_f32_16x16x32_bf16 v[44:47], v[170:173], v[186:189], v[44:47]
	v_mfma_f32_16x16x32_bf16 v[40:43], v[156:159], v[194:197], v[40:43]
	v_mfma_f32_16x16x32_bf16 v[36:39], v[170:173], v[194:197], v[36:39]
	v_mfma_f32_16x16x32_bf16 v[28:31], v[156:159], v[202:205], v[28:31]
	v_mfma_f32_16x16x32_bf16 v[24:27], v[170:173], v[202:205], v[24:27]
	v_mfma_f32_16x16x32_bf16 v[60:63], v[166:169], v[182:185], v[60:63]
	v_mfma_f32_16x16x32_bf16 v[56:59], v[174:177], v[182:185], v[56:59]
	v_mfma_f32_16x16x32_bf16 v[48:51], v[166:169], v[190:193], v[48:51]
	v_mfma_f32_16x16x32_bf16 v[44:47], v[174:177], v[190:193], v[44:47]
	v_mfma_f32_16x16x32_bf16 v[40:43], v[166:169], v[198:201], v[40:43]
	v_mfma_f32_16x16x32_bf16 v[36:39], v[174:177], v[198:201], v[36:39]
	v_mfma_f32_16x16x32_bf16 v[28:31], v[166:169], v[206:209], v[28:31]
	v_mfma_f32_16x16x32_bf16 v[24:27], v[174:177], v[206:209], v[24:27]
	s_barrier
	s_cmp_ge_u32 s30, s2
	s_cbranch_scc1 .LBB0_1591

; #define LAS __attribute__((address_space(3)))
; __device__ __forceinline__ void weights_pass(const Args& a, LAS unsigned char* scr, int gw, int NGW, int lane, int pass) {
;     unsigned char* ws = a.ws;
;     constexpr int I_IN = 64 * 72, I_PL = 64, I_OUT = 64 * 64, I_QM = 64 * 8, I_OMI = 8 * 64, I_G = 64 * 172, I_DN = 172 * 64;
;     constexpr int PER_LAYER = I_IN + I_OUT + 3 * I_QM + I_OMI + 2 * I_G + I_DN;
;     for (int it = gw + (pass == 1 ? PER_LAYER : 0); it < (pass == 2 ? PER_LAYER : 2 * PER_LAYER); it += NGW) {
;         const int l = it / PER_LAYER; int r = it % PER_LAYER;
;         { const bool shared = (r >= I_IN + I_OUT / 2 && r < I_IN + I_OUT) || (r >= I_IN + I_OUT + I_QM && r < I_IN + I_OUT + 3 * I_QM);
;           const int ip = (shared || (l == 0 && r < I_IN)) ? 0 : (l == 0 ? 2 : 1);
;           if (ip != pass) continue; }
;         unsigned char* wl = ws + WS_W + (size_t)l * WL_SIZE;
;         if (r < I_IN) { transpose_item<1>(a.in[I_WIN] + (size_t)l * DM * INW, DM, INW, (bf16_t*)(wl + WL_IN), a.in[I_GMIX] + l * DM, nullptr, 0, scr, r, lane); continue; } r -= I_IN;
;         if (r < I_OUT / 2) { transpose_item<0>(a.in[I_WOUT] + (size_t)l * DM * DM, 2048, DM, (bf16_t*)(wl + WL_OUT), nullptr, nullptr, 0, scr, r, lane, DM); continue; } r -= I_OUT / 2;
;         if (r < I_OUT / 2) { transpose_item<0>(a.in[I_WOUT] + (size_t)l * DM * DM + (size_t)2048 * DM, 2048, DM, (bf16_t*)(ws + WS_WLOW) + (size_t)l * DM * 2048, nullptr, nullptr, 0, scr, r, lane); continue; } r -= I_OUT / 2;
;         if (r < I_QM) { transpose_item<0>(a.in[I_WQM] + (size_t)l * DM * MW, DM, MW, (bf16_t*)(wl + WL_Q), a.in[I_GCROSS] + l * DM, nullptr, 0, scr, r, lane); continue; } r -= I_QM;
;         if (r < I_QM) { transpose_item<1>(a.in[I_WKM] + (size_t)l * DM * MW, DM, MW, (bf16_t*)(ws + WS_WKV) + (size_t)l * 1024 * DM, a.in[I_GMEM] + l * DM, nullptr, 0, scr, r, lane); continue; } r -= I_QM;
;         if (r < I_QM) { transpose_item<1>(a.in[I_WVM] + (size_t)l * DM * MW, DM, MW, (bf16_t*)(ws + WS_WKV) + (size_t)l * 1024 * DM, a.in[I_GMEM] + l * DM, nullptr, 512, scr, r, lane); continue; } r -= I_QM;
;         if (r < I_OMI) { transpose_item<0>(a.in[I_WOM] + (size_t)l * MW * DM, MW, DM, (bf16_t*)(wl + WL_OM), nullptr, nullptr, 0, scr, r, lane); continue; } r -= I_OMI;
.LBB0_1668:
	s_mul_hi_i32 s0, s10, 0xbfa02fe9
	s_add_i32 s0, s0, s10
	s_lshr_b32 s1, s0, 31
	s_ashr_i32 s0, s0, 15
	s_add_i32 s0, s0, s1
	s_mul_i32 s1, s0, 0xffff5500
	s_add_i32 s21, s10, s1
	s_add_i32 s23, s21, 0xffffe600
	s_cmpk_lt_u32 s23, 0x800
	s_cselect_b64 s[2:3], -1, 0
	s_and_b32 s1, s21, 0xfffffc00
	s_cmpk_eq_i32 s1, 0x2400
	s_cselect_b64 s[6:7], -1, 0
	s_or_b64 s[2:3], s[2:3], s[6:7]
	s_add_i32 s1, s10, 0xffff5500
	s_cmp_gt_u32 s1, 0xfffeaa00
	s_cselect_b64 s[6:7], -1, 0
	s_or_b64 s[2:3], s[6:7], s[2:3]
	s_and_b64 vcc, exec, s[2:3]
	s_cbranch_vccnz .LBB0_1667
	s_ashr_i32 s1, s0, 31
	s_mul_i32 s3, s0, 0x15000000
	v_readlane_b32 s6, v251, 12
	s_mul_hi_i32 s2, s0, 0x15000000
	s_add_u32 s19, s6, s3
	v_readlane_b32 s3, v251, 13
	s_addc_u32 s20, s3, s2
	s_cmpk_gt_i32 s21, 0x11ff
	s_mov_b64 s[6:7], -1
	s_cbranch_scc0 .LBB0_1713
	s_cmpk_gt_u32 s21, 0x19ff
	s_cbranch_scc0 .LBB0_1710
	s_cmpk_gt_u32 s21, 0x21ff
	s_cbranch_scc0 .LBB0_1707
	s_cmpk_gt_u32 s21, 0x23ff
	s_cbranch_scc0 .LBB0_1702
	s_cmpk_gt_u32 s21, 0x25ff
	s_cbranch_scc0 .LBB0_1697
	s_cmpk_gt_u32 s21, 0x27ff
	s_cbranch_scc0 .LBB0_1692
	s_cmpk_gt_u32 s21, 0x29ff
	s_cbranch_scc0 .LBB0_1689
	s_cmpk_gt_u32 s21, 0x54ff
	s_mul_hi_i32 s2, s0, 0xac00000
	s_mul_i32 s3, s0, 0xac00000
	s_cbranch_scc0 .LBB0_1684
	s_cmpk_gt_u32 s21, 0x7fff
	s_cbranch_scc0 .LBB0_1679
	v_readlane_b32 s36, v255, 11
	s_nop 3
	s_cmpk_eq_i32 s36, 0x100
	s_cbranch_scc1 .LBB0_1667
	v_readlane_b32 s36, v250, 0
	v_readlane_b32 s42, v250, 6
	v_readlane_b32 s43, v250, 7
	s_add_u32 s8, s42, s3
	s_addc_u32 s9, s43, s2
	s_and_b32 s6, s21, 0xffc0
	s_xor_b32 s7, s6, 0x8000
	s_lshl_b32 s6, s21, 6
	v_lshlrev_b32_e32 v4, 2, v3
	s_and_b32 s6, s6, 0xfc0
	v_lshl_or_b32 v4, s7, 14, v4
	v_mov_b32_e32 v5, v2
	v_lshl_add_u64 v[4:5], s[8:9], 0, v[4:5]
	s_lshl_b32 s14, s6, 2
	v_lshl_add_u64 v[4:5], v[4:5], 0, s[14:15]
	v_lshlrev_b32_e32 v6, 2, v68
	v_mov_b32_e32 v7, v2
	v_lshl_add_u64 v[60:61], v[4:5], 0, v[6:7]
	s_movk_i32 s8, 0x4000
	v_add_co_u32_e32 v8, vcc, s8, v60
	s_mov_b32 s8, 0x24000
	s_nop 0
	v_addc_co_u32_e32 v9, vcc, 0, v61, vcc
	global_load_dwordx4 v[4:7], v[60:61], off nt
	s_nop 0
	global_load_dwordx4 v[8:11], v[8:9], off nt
	v_add_co_u32_e32 v12, vcc, s22, v60
	s_lshl_b32 s7, s7, 1
	s_nop 0
	v_addc_co_u32_e32 v13, vcc, 0, v61, vcc
	v_add_co_u32_e32 v16, vcc, s8, v60
	s_mov_b32 s8, 0x40000
	s_nop 0
	v_addc_co_u32_e32 v17, vcc, 0, v61, vcc
	global_load_dwordx4 v[12:15], v[12:13], off nt
	s_nop 0
	global_load_dwordx4 v[16:19], v[16:17], off nt
	v_add_co_u32_e32 v20, vcc, s8, v60
	s_mov_b32 s8, 0x44000
	s_nop 0
	v_addc_co_u32_e32 v21, vcc, 0, v61, vcc
	v_add_co_u32_e32 v24, vcc, s8, v60
	s_mov_b32 s8, 0x60000
	s_nop 0
	v_addc_co_u32_e32 v25, vcc, 0, v61, vcc
	global_load_dwordx4 v[20:23], v[20:21], off nt
	s_nop 0
	global_load_dwordx4 v[24:27], v[24:25], off nt
	v_add_co_u32_e32 v28, vcc, s8, v60
	s_mov_b32 s8, 0x64000
	s_nop 0
	v_addc_co_u32_e32 v29, vcc, 0, v61, vcc
	v_add_co_u32_e32 v32, vcc, s8, v60
	s_mov_b32 s8, 0x80000
	s_nop 0
	v_addc_co_u32_e32 v33, vcc, 0, v61, vcc
	global_load_dwordx4 v[28:31], v[28:29], off nt
	s_nop 0
	global_load_dwordx4 v[32:35], v[32:33], off nt
	v_add_co_u32_e32 v36, vcc, s8, v60
	s_mov_b32 s8, 0x84000
	s_nop 0
	v_addc_co_u32_e32 v37, vcc, 0, v61, vcc
	v_add_co_u32_e32 v40, vcc, s8, v60
	s_mov_b32 s8, 0xa0000
	s_nop 0
	v_addc_co_u32_e32 v41, vcc, 0, v61, vcc
	global_load_dwordx4 v[36:39], v[36:37], off nt
	s_nop 0
	global_load_dwordx4 v[40:43], v[40:41], off nt
	v_add_co_u32_e32 v44, vcc, s8, v60
	s_mov_b32 s8, 0xa4000
	s_nop 0
	v_addc_co_u32_e32 v45, vcc, 0, v61, vcc
	v_add_co_u32_e32 v48, vcc, s8, v60
	s_mov_b32 s8, 0xc0000
	s_nop 0
	v_addc_co_u32_e32 v49, vcc, 0, v61, vcc
	global_load_dwordx4 v[44:47], v[44:45], off nt
	s_nop 0
	global_load_dwordx4 v[48:51], v[48:49], off nt
	v_add_co_u32_e32 v52, vcc, s8, v60
	s_mov_b32 s8, 0xc4000
	s_nop 0
	v_addc_co_u32_e32 v53, vcc, 0, v61, vcc
	v_add_co_u32_e32 v56, vcc, s8, v60
	s_mov_b32 s8, 0xe0000
	s_nop 0
	v_addc_co_u32_e32 v57, vcc, 0, v61, vcc
	global_load_dwordx4 v[52:55], v[52:53], off nt
	s_nop 0
	global_load_dwordx4 v[56:59], v[56:57], off nt
	v_add_co_u32_e32 v62, vcc, s8, v60
	s_mov_b32 s8, 0xe4000
	s_nop 0
	v_addc_co_u32_e32 v63, vcc, 0, v61, vcc
	v_add_co_u32_e32 v64, vcc, s8, v60
	s_add_u32 s8, s19, s7
	s_nop 0
	v_addc_co_u32_e32 v65, vcc, 0, v61, vcc
	global_load_dwordx4 v[60:63], v[62:63], off nt
	s_nop 0
	global_load_dwordx4 v[64:67], v[64:65], off nt
	s_waitcnt vmcnt(0)
; #define LAS __attribute__((address_space(3)))
; #define LDS_WAIT() asm volatile("s_waitcnt lgkmcnt(0)" ::: "memory")
; __device__ __forceinline__ unsigned cvt_pk_bf16(float lo, float hi) { unsigned r; asm volatile("v_cvt_pk_bf16_f32 %0, %1, %2" : "=v"(r) : "v"(lo), "v"(hi)); return r; }
;     ...
; #pragma unroll
;     for (int i = 0; i < 8; ++i)
; #pragma unroll
;         for (int e = 0; e < 4; ++e) *(LAS unsigned*)(scr + (4 * r16 + e) * 128 + ((i ^ (r16 & 7)) * 16) + q * 4) = cvt_pk_bf16(v[2 * i][e], v[2 * i + 1][e]);
;     LDS_WAIT(); asm volatile("" ::: "memory");
;     const int c = lane & 7;
; #pragma unroll
;     for (int j = 0; j < 8; ++j) { const int row = (lane >> 3) + 8 * j; const u32x4 o = *(const LAS u32x4*)(scr + row * 128 + ((c ^ ((row >> 2) & 7)) * 16));
;         const int lc = col_off + n0 + row; int dr;
;         if (MODE == 0) dr = lc;
;         else if (MODE == 1) dr = (lc & ~255) + 128 * ((lc >> 5) & 1) + 32 * ((lc >> 6) & 3) + (lc & 31);
;         else if (MODE == 2) dr = 256 * (lc >> 7) + (lc & 127);
;         else dr = 256 * (lc >> 7) + 128 + (lc & 127);
;         *(u32x4*)(WT + (size_t)dr * (ldt ? ldt : K) + k0 + 8 * c) = o; }
;     LDS_WAIT(); asm volatile("" ::: "memory");
	v_cvt_pk_bf16_f32 v4, v4, v8
	v_add_u32_e32 v8, v69, v71
	ds_write_b32 v8, v4
	v_cvt_pk_bf16_f32 v4, v5, v9
	ds_write_b32 v8, v4 offset:128
	v_cvt_pk_bf16_f32 v4, v6, v10
	ds_write_b32 v8, v4 offset:256
	v_cvt_pk_bf16_f32 v4, v7, v11
	ds_write_b32 v8, v4 offset:384
	v_cvt_pk_bf16_f32 v4, v12, v16
	v_add_u32_e32 v5, v73, v71
	ds_write_b32 v5, v4
	v_cvt_pk_bf16_f32 v4, v13, v17
	ds_write_b32 v5, v4 offset:128
	v_cvt_pk_bf16_f32 v4, v14, v18
	ds_write_b32 v5, v4 offset:256
	v_cvt_pk_bf16_f32 v4, v15, v19
	ds_write_b32 v5, v4 offset:384
	v_cvt_pk_bf16_f32 v4, v20, v24
	v_add_u32_e32 v5, v74, v71
	ds_write_b32 v5, v4
	v_cvt_pk_bf16_f32 v4, v21, v25
	ds_write_b32 v5, v4 offset:128
	v_cvt_pk_bf16_f32 v4, v22, v26
	ds_write_b32 v5, v4 offset:256
	v_cvt_pk_bf16_f32 v4, v23, v27
	ds_write_b32 v5, v4 offset:384
	v_cvt_pk_bf16_f32 v4, v28, v32
	v_add_u32_e32 v5, v75, v71
	ds_write_b32 v5, v4
	v_cvt_pk_bf16_f32 v4, v29, v33
	ds_write_b32 v5, v4 offset:128
	v_cvt_pk_bf16_f32 v4, v30, v34
	ds_write_b32 v5, v4 offset:256
	v_cvt_pk_bf16_f32 v4, v31, v35
	ds_write_b32 v5, v4 offset:384
	v_cvt_pk_bf16_f32 v4, v36, v40
	v_add_u32_e32 v5, v76, v71
	ds_write_b32 v5, v4
	v_cvt_pk_bf16_f32 v4, v37, v41
	ds_write_b32 v5, v4 offset:128
	v_cvt_pk_bf16_f32 v4, v38, v42
	ds_write_b32 v5, v4 offset:256
	v_cvt_pk_bf16_f32 v4, v39, v43
	ds_write_b32 v5, v4 offset:384
	v_cvt_pk_bf16_f32 v4, v44, v48
	v_add_u32_e32 v5, v77, v71
	ds_write_b32 v5, v4
	v_cvt_pk_bf16_f32 v4, v45, v49
	ds_write_b32 v5, v4 offset:128
	v_cvt_pk_bf16_f32 v4, v46, v50
	ds_write_b32 v5, v4 offset:256
	v_cvt_pk_bf16_f32 v4, v47, v51
	ds_write_b32 v5, v4 offset:384
	v_cvt_pk_bf16_f32 v4, v52, v56
	v_add_u32_e32 v5, v78, v71
	ds_write_b32 v5, v4
	v_cvt_pk_bf16_f32 v4, v53, v57
	ds_write_b32 v5, v4 offset:128
	v_cvt_pk_bf16_f32 v4, v54, v58
	ds_write_b32 v5, v4 offset:256
	v_cvt_pk_bf16_f32 v4, v55, v59
	ds_write_b32 v5, v4 offset:384
	v_cvt_pk_bf16_f32 v4, v60, v64
	v_add_u32_e32 v5, v79, v71
	ds_write_b32 v5, v4
	v_cvt_pk_bf16_f32 v4, v61, v65
	ds_write_b32 v5, v4 offset:128
	v_cvt_pk_bf16_f32 v4, v62, v66
	ds_write_b32 v5, v4 offset:256
	v_cvt_pk_bf16_f32 v4, v63, v67
	ds_write_b32 v5, v4 offset:384
	s_addc_u32 s9, s20, 0
	v_lshlrev_b32_e32 v4, 1, v70
	v_mov_b32_e32 v5, v2
	s_waitcnt lgkmcnt(0)
	v_lshl_add_u64 v[4:5], s[8:9], 0, v[4:5]
	s_mov_b64 s[8:9], 0xfa00000
	v_lshl_add_u64 v[12:13], v[4:5], 0, s[8:9]
	v_add_u32_e32 v4, v81, v82
	ds_read_b128 v[4:7], v4
	v_or_b32_e32 v8, s6, v80
	v_mul_u32_u24_e32 v8, 0x2b00, v8
	v_lshlrev_b32_e32 v8, 1, v8
	v_mov_b32_e32 v9, v2
	v_lshl_add_u64 v[14:15], v[12:13], 0, v[8:9]
	v_add_u32_e32 v8, v84, v85
	ds_read_b128 v[8:11], v8
	s_waitcnt lgkmcnt(1)
	global_store_dwordx4 v[14:15], v[4:7], off
	v_readlane_b32 s37, v250, 1
	v_readlane_b32 s38, v250, 2
	v_or_b32_e32 v4, s6, v83
	v_mul_u32_u24_e32 v4, 0x2b00, v4
	v_lshlrev_b32_e32 v4, 1, v4
	v_mov_b32_e32 v5, v2
	v_lshl_add_u64 v[4:5], v[12:13], 0, v[4:5]
	s_waitcnt lgkmcnt(0)
	global_store_dwordx4 v[4:5], v[8:11], off
	v_add_u32_e32 v4, v87, v88
	ds_read_b128 v[4:7], v4
	v_or_b32_e32 v8, s6, v86
	v_mul_u32_u24_e32 v8, 0x2b00, v8
	v_lshlrev_b32_e32 v8, 1, v8
	v_mov_b32_e32 v9, v2
	v_lshl_add_u64 v[14:15], v[12:13], 0, v[8:9]
	v_add_u32_e32 v8, v90, v91
	ds_read_b128 v[8:11], v8
	s_waitcnt lgkmcnt(1)
	global_store_dwordx4 v[14:15], v[4:7], off
	v_readlane_b32 s39, v250, 3
	v_readlane_b32 s40, v250, 4
	v_or_b32_e32 v4, s6, v89
	v_mul_u32_u24_e32 v4, 0x2b00, v4
	v_lshlrev_b32_e32 v4, 1, v4
	v_mov_b32_e32 v5, v2
	v_lshl_add_u64 v[4:5], v[12:13], 0, v[4:5]
	s_waitcnt lgkmcnt(0)
	global_store_dwordx4 v[4:5], v[8:11], off
	v_add_u32_e32 v4, v93, v82
	ds_read_b128 v[4:7], v4
	v_or_b32_e32 v8, s6, v92
	v_mul_u32_u24_e32 v8, 0x2b00, v8
	v_lshlrev_b32_e32 v8, 1, v8
	v_mov_b32_e32 v9, v2
	v_lshl_add_u64 v[14:15], v[12:13], 0, v[8:9]
	v_add_u32_e32 v8, v95, v96
	ds_read_b128 v[8:11], v8
	s_waitcnt lgkmcnt(1)
	global_store_dwordx4 v[14:15], v[4:7], off
	v_readlane_b32 s41, v250, 5
	s_nop 0
	v_or_b32_e32 v4, s6, v94
	v_mul_u32_u24_e32 v4, 0x2b00, v4
	v_lshlrev_b32_e32 v4, 1, v4
	v_mov_b32_e32 v5, v2
	v_lshl_add_u64 v[4:5], v[12:13], 0, v[4:5]
	s_waitcnt lgkmcnt(0)
	global_store_dwordx4 v[4:5], v[8:11], off
	v_add_u32_e32 v4, v98, v99
	ds_read_b128 v[4:7], v4
	v_or_b32_e32 v8, s6, v97
	v_mul_u32_u24_e32 v8, 0x2b00, v8
	v_lshlrev_b32_e32 v8, 1, v8
	v_mov_b32_e32 v9, v2
	v_lshl_add_u64 v[14:15], v[12:13], 0, v[8:9]
	v_add_u32_e32 v8, v101, v102
	ds_read_b128 v[8:11], v8
	s_waitcnt lgkmcnt(1)
	global_store_dwordx4 v[14:15], v[4:7], off
	s_nop 1
	v_or_b32_e32 v4, s6, v100
	v_mul_u32_u24_e32 v4, 0x2b00, v4
	v_lshlrev_b32_e32 v4, 1, v4
	v_mov_b32_e32 v5, v2
	v_lshl_add_u64 v[4:5], v[12:13], 0, v[4:5]
	s_waitcnt lgkmcnt(0)
	global_store_dwordx4 v[4:5], v[8:11], off
	s_waitcnt lgkmcnt(0)
	s_mov_b64 s[6:7], 0
